# ret_kv state stores widened: v_permlane16_swap pairs tiles (t,t+1) so each lane stores 16 contiguous bytes; 16 dwordx2 stores per lane become 8 dwordx4 (same bytes, same addresses)
# speedup vs baseline: 1.0047x; 1.0011x over previous
; DI int lbid() { int b = (int)blockIdx.x; asm volatile("" : "+s"(b)); return b; }
; DI int lgdim() { int g = (int)gridDim.x; asm volatile("" : "+s"(g)); return g; }
; DI float ret_log2gamma(const Params& P, int dir, int h) { const float de = P.ret_decay[dir * NTH + h]; return log1pf(-exp2f(-de)) * LOG2E; }
; DI void ret_kv_phase(const Params& P, LAS unsigned char* lds, int r, const bf16* QKV, bf16* ST) {
;     ...
;     for (int u = lbid(); u < 128 * NTH; u += lgdim()) {
;         int g = g0, li = li0; asm volatile("" : "+v"(g), "+v"(li));
;         const int n = u / NTH, h = u % NTH;
;         const int tokbase = n * 128, pos0 = (n % cps) * 128;
;         const float l2f = ret_log2gamma(P, 0, h), l2b = ret_log2gamma(P, 1, h);
.LBB0_249:
	s_mul_hi_i32 s4, s0, 0x2aaaaaab
	s_lshr_b32 s5, s4, 31
	s_ashr_i32 s9, s4, 1
	s_add_i32 s9, s9, s5
	s_abs_i32 s5, s9
	s_mul_hi_u32 s7, s5, s3
	s_mul_i32 s7, s7, s1
	s_mul_i32 s8, s9, 12
	s_sub_i32 s5, s5, s7
	s_sub_i32 s6, s0, s8
	s_lshl_b32 s10, s9, 7
	s_ashr_i32 s4, s9, 31
	s_sub_i32 s7, s5, s1
	s_cmp_ge_u32 s5, s1
	s_cselect_b32 s5, s7, s5
	s_sub_i32 s7, s5, s1
	s_cmp_ge_u32 s5, s1
	s_cselect_b32 s5, s7, s5
	s_xor_b32 s5, s5, s4
	s_sub_i32 s4, s5, s4
	s_ashr_i32 s7, s6, 31
	s_lshl_b32 s11, s4, 7
	s_lshl_b64 s[4:5], s[6:7], 2
	s_add_u32 s4, s50, s4
	s_addc_u32 s5, s51, s5
	v_mov_b32_e32 v28, v8
	v_mov_b32_e32 v29, v9
	v_mov_b64_e32 v[6:7], s[4:5]
	flat_load_dword v5, v[6:7]
	s_nop 0
	flat_load_dword v6, v[6:7] offset:48
	s_waitcnt vmcnt(0) lgkmcnt(0)
	v_cmp_lt_f32_e32 vcc, s14, v5
	s_nop 1
	v_cndmask_b32_e32 v7, 0, v166, vcc
	v_cmp_lt_f32_e64 s[4:5], s14, v6
	v_sub_f32_e32 v5, v7, v5
	v_exp_f32_e32 v5, v5
	v_cndmask_b32_e64 v30, 0, v166, s[4:5]
	v_sub_f32_e32 v6, v30, v6
	v_exp_f32_e32 v6, v6
	v_cndmask_b32_e32 v7, 0, v167, vcc
	v_ldexp_f32 v5, v5, v7
	v_cndmask_b32_e64 v30, 0, v167, s[4:5]
	v_sub_f32_e32 v32, 1.0, v5
	v_ldexp_f32 v68, v6, v30
	v_frexp_mant_f32_e32 v35, v32
	v_cvt_f64_f32_e32 v[6:7], v32
	v_sub_f32_e32 v33, 1.0, v68
	v_add_f32_e32 v34, -1.0, v32
	v_frexp_exp_i32_f64_e32 v6, v[6:7]
	v_cmp_gt_f32_e32 vcc, s15, v35
	v_add_f32_e32 v36, -1.0, v33
	v_frexp_mant_f32_e32 v37, v33
	v_cvt_f64_f32_e32 v[30:31], v33
	v_sub_f32_e32 v38, v34, v32
	v_subbrev_co_u32_e32 v6, vcc, 0, v6, vcc
	v_sub_f32_e64 v34, -v5, v34
	v_sub_f32_e32 v7, v36, v33
	v_frexp_exp_i32_f64_e32 v30, v[30:31]
	v_add_f32_e32 v31, 1.0, v38
	v_cmp_gt_f32_e32 vcc, s15, v37
	v_sub_f32_e64 v36, -v68, v36
	v_add_f32_e32 v7, 1.0, v7
	v_subbrev_co_u32_e32 v58, vcc, 0, v30, vcc
	v_add_f32_e32 v30, v34, v31
	v_sub_u32_e32 v31, 0, v6
	v_add_f32_e32 v7, v36, v7
	v_sub_u32_e32 v34, 0, v58
	v_ldexp_f32 v32, v32, v31
	v_ldexp_f32 v42, v33, v34
	v_ldexp_f32 v43, v7, v34
	v_add_f32_e32 v7, -1.0, v32
	v_add_f32_e32 v33, 1.0, v32
	v_ldexp_f32 v30, v30, v31
	v_add_f32_e32 v44, -1.0, v42
	v_add_f32_e32 v31, 1.0, v7
	v_add_f32_e32 v34, -1.0, v33
	v_add_f32_e32 v35, 1.0, v44
	v_sub_f32_e32 v31, v32, v31
	v_sub_f32_e32 v32, v32, v34
	v_sub_f32_e32 v34, v42, v35
	v_add_f32_e32 v35, v30, v31
	v_add_f32_e32 v30, v30, v32
	v_add_f32_e32 v36, v33, v30
	v_rcp_f32_e32 v37, v36
	v_add_f32_e32 v31, v7, v35
	v_sub_f32_e32 v32, v36, v33
	v_sub_f32_e32 v38, v30, v32
	v_mul_f32_e32 v39, v31, v37
	v_mul_f32_e32 v32, v36, v39
	v_add_f32_e32 v45, v43, v34
	v_fma_f32 v34, v39, v36, -v32
	v_fmac_f32_e32 v34, v39, v38
	v_add_f32_e32 v30, v32, v34
	v_sub_f32_e32 v7, v31, v7
	v_sub_f32_e32 v33, v31, v30
	v_sub_f32_e32 v7, v35, v7
	v_mov_b32_e32 v35, v30
	v_pk_add_f32 v[30:31], v[30:31], v[32:33] neg_lo:[0,1] neg_hi:[0,1]
	v_cvt_f32_i32_e32 v6, v6
	v_pk_add_f32 v[30:31], v[30:31], v[34:35] neg_lo:[0,1] neg_hi:[0,1]
	v_cmp_nlt_f32_e32 vcc, 1.0, v5
	v_add_f32_e32 v7, v7, v31
	v_add_f32_e32 v7, v30, v7
	v_add_f32_e32 v31, v33, v7
	v_mul_f32_e32 v30, v37, v31
	v_mul_f32_e32 v32, v36, v30
	v_sub_f32_e32 v33, v33, v31
	v_add_f32_e32 v40, v39, v30
	v_fma_f32 v34, v30, v36, -v32
	v_add_f32_e32 v7, v7, v33
	v_sub_f32_e32 v33, v40, v39
	v_fmac_f32_e32 v34, v30, v38
	v_sub_f32_e32 v36, v30, v33
	v_add_f32_e32 v30, v32, v34
	v_sub_f32_e32 v33, v31, v30
	v_mov_b32_e32 v35, v30
	v_pk_add_f32 v[30:31], v[30:31], v[32:33] neg_lo:[0,1] neg_hi:[0,1]
	v_cmp_lt_f32_e64 s[4:5], |v5|, s17
	v_pk_add_f32 v[30:31], v[30:31], v[34:35] neg_lo:[0,1] neg_hi:[0,1]
	s_nop 0
	v_add_f32_e32 v7, v7, v31
	v_add_f32_e32 v7, v30, v7
	v_add_f32_e32 v7, v33, v7
	v_mul_f32_e32 v7, v37, v7
	v_add_f32_e32 v7, v36, v7
	v_add_f32_e32 v30, v40, v7
	v_mul_f32_e32 v32, v30, v30
	v_sub_f32_e32 v33, v30, v40
	v_fmamk_f32 v34, v32, 0x3e9b6dac, v155
	v_sub_f32_e32 v33, v7, v33
	v_mul_f32_e32 v7, v30, v32
	v_fmaak_f32 v131, v32, v34, 0x3f2aaada
	v_ldexp_f32 v35, v33, 1
	v_pk_mul_f32 v[32:33], v[6:7], v[130:131]
	v_ldexp_f32 v31, v30, 1
	v_fma_f32 v30, v6, s16, -v32
	v_fmac_f32_e32 v30, 0xb102e308, v6
	v_pk_add_f32 v[6:7], v[32:33], v[30:31]
	v_mov_b32_e32 v34, v32
	v_sub_f32_e32 v38, v7, v31
	v_pk_add_f32 v[36:37], v[6:7], v[32:33] neg_lo:[0,1] neg_hi:[0,1]
	v_sub_f32_e32 v32, v33, v38
	v_add_f32_e32 v35, v35, v32
	v_pk_add_f32 v[32:33], v[6:7], v[34:35]
	v_mov_b32_e32 v31, v6
	v_mov_b32_e32 v37, v33
	v_pk_add_f32 v[40:41], v[30:31], v[36:37] neg_lo:[0,1] neg_hi:[0,1]
	v_pk_add_f32 v[30:31], v[30:31], v[36:37]
	v_mov_b32_e32 v39, v6
	v_pk_add_f32 v[36:37], v[30:31], v[6:7] op_sel:[1,0] op_sel_hi:[0,1] neg_lo:[0,1] neg_hi:[0,1]
	v_mov_b32_e32 v38, v35
	v_mov_b32_e32 v34, v33
	v_mov_b32_e32 v35, v31
	v_pk_mov_b32 v[6:7], v[6:7], v[36:37] op_sel:[1,0]
	v_pk_add_f32 v[32:33], v[32:33], v[36:37] op_sel_hi:[1,0] neg_lo:[0,1] neg_hi:[0,1]
	v_pk_add_f32 v[6:7], v[34:35], v[6:7] neg_lo:[0,1] neg_hi:[0,1]
	v_mov_b32_e32 v32, v40
	v_pk_add_f32 v[6:7], v[38:39], v[6:7] neg_lo:[0,1] neg_hi:[0,1]
	v_mov_b32_e32 v41, v31
	v_pk_add_f32 v[32:33], v[32:33], v[6:7]
	v_add_u32_e32 v38, s11, v11
	v_pk_add_f32 v[34:35], v[32:33], v[32:33] op_sel:[0,1] op_sel_hi:[1,0]
	v_ashrrev_i32_e32 v39, 31, v38
	v_pk_add_f32 v[30:31], v[30:31], v[34:35] op_sel:[1,0] op_sel_hi:[0,1]
	v_mov_b32_e32 v33, v30
	v_mov_b32_e32 v7, v34
	v_pk_add_f32 v[34:35], v[32:33], v[40:41] neg_lo:[0,1] neg_hi:[0,1]
	v_lshlrev_b64 v[38:39], 8, v[38:39]
	v_sub_f32_e32 v31, v32, v34
	v_pk_add_f32 v[6:7], v[6:7], v[34:35] neg_lo:[0,1] neg_hi:[0,1]
	v_sub_f32_e32 v31, v40, v31
	v_add_f32_e32 v6, v6, v31
	v_add_f32_e32 v6, v6, v7
	v_add_f32_e32 v6, v30, v6
	v_cndmask_b32_e32 v6, v168, v6, vcc
; #define LAS __attribute__((address_space(3)))
; DI unsigned pk2(float lo, float hi) { return pg8::cvt_pk_bf16(lo, hi); }
; DI float fexp2(float x) { return __builtin_amdgcn_exp2f(x); }
; DI void ret_kv_phase(const Params& P, LAS unsigned char* lds, int r, const bf16* QKV, bf16* ST) {
;     ...
;         _Pragma("unroll") for (int it_ = 0; it_ < 2; ++it_) { const int task = tid + 512 * it_; const int j = task >> 3, dg = task & 7;
;             const bf16* kp = QKV + (size_t)(tokbase + j) * NIN0 + 1536 + h * 128 + dg * 8;
;             const bf16x8 lo = *(const bf16x8*)kp, hi = *(const bf16x8*)(kp + 64);
;             const float* cp = rc + (size_t)(pos0 + j) * 64 + dg * 8; const float* sp = rsn + (size_t)(pos0 + j) * 64 + dg * 8;
;             const f32x4 c0 = *(const f32x4*)cp, c1 = *(const f32x4*)(cp + 4), s0 = *(const f32x4*)sp, s1 = *(const f32x4*)(sp + 4);
;             const float wf = QK_SCALE * fexp2((float)(127 - j) * l2f), wb = QK_SCALE * fexp2((float)j * l2b);
;             float o1[8], o2[8];
; #pragma unroll
;             for (int e = 0; e < 8; ++e) { const float x1 = bf2f((unsigned short)lo[e]), x2 = bf2f((unsigned short)hi[e]); const float c = e < 4 ? c0[e & 3] : c1[e & 3], s = e < 4 ? s0[e & 3] : s1[e & 3];
;                 o1[e] = x1 * c - x2 * s; o2[e] = x1 * s + x2 * c; }
;             v4u a, b, c, d;
;             a.x = pk2(o1[0] * wf, o1[1] * wf); a.y = pk2(o1[2] * wf, o1[3] * wf); a.z = pk2(o1[4] * wf, o1[5] * wf); a.w = pk2(o1[6] * wf, o1[7] * wf);
;             b.x = pk2(o2[0] * wf, o2[1] * wf); b.y = pk2(o2[2] * wf, o2[3] * wf); b.z = pk2(o2[4] * wf, o2[5] * wf); b.w = pk2(o2[6] * wf, o2[7] * wf);
;             c.x = pk2(o1[0] * wb, o1[1] * wb); c.y = pk2(o1[2] * wb, o1[3] * wb); c.z = pk2(o1[4] * wb, o1[5] * wb); c.w = pk2(o1[6] * wb, o1[7] * wb);
;             d.x = pk2(o2[0] * wb, o2[1] * wb); d.y = pk2(o2[2] * wb, o2[3] * wb); d.z = pk2(o2[4] * wb, o2[5] * wb); d.w = pk2(o2[6] * wb, o2[7] * wb);
;             *(LAS v4u*)(KF + j * PITCH + dg * 16) = a; *(LAS v4u*)(KF + j * PITCH + 128 + dg * 16) = b;
;             *(LAS v4u*)(KB + j * PITCH + dg * 16) = c; *(LAS v4u*)(KB + j * PITCH + 128 + dg * 16) = d; }
	v_cmp_neq_f32_e32 vcc, 1.0, v5
	v_lshl_add_u64 v[54:55], v[2:3], 0, v[38:39]
	v_lshl_add_u64 v[52:53], v[0:1], 0, v[38:39]
	v_cndmask_b32_e32 v6, v169, v6, vcc
	v_cndmask_b32_e64 v5, v6, -v5, s[4:5]
	v_add_f32_e32 v6, 1.0, v42
	v_add_f32_e32 v7, -1.0, v6
	v_sub_f32_e32 v7, v42, v7
	v_add_f32_e32 v7, v43, v7
	v_add_f32_e32 v34, v6, v7
	v_rcp_f32_e32 v59, v34
	v_sub_f32_e32 v6, v34, v6
	v_sub_f32_e32 v48, v7, v6
	v_add_f32_e32 v7, v44, v45
	v_mul_f32_e32 v60, v7, v59
	v_mul_f32_e32 v46, v34, v60
	v_fma_f32 v30, v60, v34, -v46
	v_sub_f32_e32 v6, v7, v44
	v_fmac_f32_e32 v30, v60, v48
	v_sub_f32_e32 v35, v45, v6
	v_add_f32_e32 v6, v46, v30
	v_sub_f32_e32 v47, v7, v6
	v_pk_add_f32 v[32:33], v[6:7], v[46:47] neg_lo:[0,1] neg_hi:[0,1]
	v_mov_b32_e32 v31, v6
	v_pk_add_f32 v[6:7], v[32:33], v[30:31] neg_lo:[0,1] neg_hi:[0,1]
	s_lshl_b32 s4, s6, 7
	v_add_f32_e32 v7, v35, v7
	v_add_f32_e32 v51, v6, v7
	v_add_f32_e32 v49, v47, v51
	v_mul_f32_e32 v61, v59, v49
	v_mul_f32_e32 v46, v34, v61
	v_fma_f32 v50, v61, v34, -v46
	v_fmac_f32_e32 v50, v61, v48
	v_sub_f32_e32 v47, v47, v49
	v_add_f32_e32 v48, v46, v50
	v_add_f32_e32 v62, v51, v47
	v_sub_f32_e32 v47, v49, v48
	v_pk_add_f32 v[56:57], v[48:49], v[46:47] neg_lo:[0,1] neg_hi:[0,1]
	v_mov_b32_e32 v51, v48
	v_pk_add_f32 v[48:49], v[56:57], v[50:51] neg_lo:[0,1] neg_hi:[0,1]
	s_ashr_i32 s5, s4, 31
	v_add_f32_e32 v46, v62, v49
	v_add_f32_e32 v46, v48, v46
	v_add_f32_e32 v46, v47, v46
	v_add_f32_e32 v47, v60, v61
	v_sub_f32_e32 v48, v47, v60
	v_mul_f32_e32 v46, v59, v46
	v_sub_f32_e32 v48, v61, v48
	v_add_u32_e32 v30, s10, v11
	v_mov_b64_e32 v[6:7], s[44:45]
	v_add_f32_e32 v48, v48, v46
	v_mad_i64_i32 v[30:31], s[12:13], v30, s18, v[6:7]
	s_lshl_b64 s[4:5], s[4:5], 1
	v_add_f32_e32 v49, v47, v48
	v_lshl_add_u64 v[30:31], v[30:31], 0, s[4:5]
	v_mul_f32_e32 v50, v49, v49
	v_lshl_add_u64 v[34:35], v[30:31], 0, v[128:129]
	v_fmamk_f32 v46, v50, 0x3e9b6dac, v155
	flat_load_dwordx4 v[30:33], v[34:35] offset:3072
	s_nop 0
	flat_load_dwordx4 v[34:37], v[34:35] offset:3200
	s_nop 0
	flat_load_dwordx4 v[38:41], v[54:55]
	flat_load_dwordx4 v[42:45], v[52:53]
	v_fmaak_f32 v131, v50, v46, 0x3f2aaada
	v_cvt_f32_i32_e32 v46, v58
	v_sub_f32_e32 v47, v49, v47
	v_sub_f32_e32 v47, v48, v47
	v_ldexp_f32 v48, v47, 1
	v_mul_f32_e32 v47, v49, v50
	v_pk_mul_f32 v[58:59], v[46:47], v[130:131]
	v_ldexp_f32 v57, v49, 1
	v_fma_f32 v56, v46, s16, -v58
	v_fmac_f32_e32 v56, 0xb102e308, v46
	v_pk_add_f32 v[60:61], v[58:59], v[56:57]
	v_mov_b32_e32 v62, v58
	v_sub_f32_e32 v46, v61, v57
	v_sub_f32_e32 v46, v59, v46
	v_add_f32_e32 v63, v48, v46
	flat_load_dwordx4 v[46:49], v[54:55] offset:16
	s_nop 0
	flat_load_dwordx4 v[50:53], v[52:53] offset:16
	v_pk_add_f32 v[54:55], v[60:61], v[58:59] neg_lo:[0,1] neg_hi:[0,1]
	v_pk_add_f32 v[58:59], v[60:61], v[62:63]
	v_mov_b32_e32 v57, v60
	v_mov_b32_e32 v55, v59
	v_pk_add_f32 v[64:65], v[56:57], v[54:55] neg_lo:[0,1] neg_hi:[0,1]
	v_pk_add_f32 v[54:55], v[56:57], v[54:55]
	v_cmp_nlt_f32_e32 vcc, 1.0, v68
	v_pk_add_f32 v[56:57], v[54:55], v[60:61] op_sel:[1,0] op_sel_hi:[0,1] neg_lo:[0,1] neg_hi:[0,1]
	v_pk_add_f32 v[66:67], v[58:59], v[56:57] op_sel_hi:[1,0] neg_lo:[0,1] neg_hi:[0,1]
	v_mov_b32_e32 v58, v59
	v_mov_b32_e32 v59, v55
	v_pk_mov_b32 v[56:57], v[60:61], v[56:57] op_sel:[1,0]
	v_mov_b32_e32 v66, v64
	v_pk_add_f32 v[56:57], v[58:59], v[56:57] neg_lo:[0,1] neg_hi:[0,1]
	v_mov_b32_e32 v58, v63
	v_mov_b32_e32 v59, v60
	v_pk_add_f32 v[56:57], v[58:59], v[56:57] neg_lo:[0,1] neg_hi:[0,1]
	v_mov_b32_e32 v65, v55
	v_pk_add_f32 v[58:59], v[66:67], v[56:57]
	v_cmp_lt_f32_e64 s[12:13], |v68|, s17
	v_pk_add_f32 v[60:61], v[58:59], v[58:59] op_sel:[0,1] op_sel_hi:[1,0]
	v_mul_f32_e32 v5, 0x3fb8aa3b, v5
	v_pk_add_f32 v[54:55], v[54:55], v[60:61] op_sel:[1,0] op_sel_hi:[0,1]
	v_mov_b32_e32 v59, v54
	v_pk_add_f32 v[62:63], v[58:59], v[64:65] neg_lo:[0,1] neg_hi:[0,1]
	v_mov_b32_e32 v57, v60
	v_sub_f32_e32 v55, v58, v62
	v_pk_add_f32 v[56:57], v[56:57], v[62:63] neg_lo:[0,1] neg_hi:[0,1]
	v_sub_f32_e32 v55, v64, v55
	v_add_f32_e32 v55, v56, v55
	v_add_f32_e32 v55, v55, v57
	v_add_f32_e32 v54, v54, v55
	v_cndmask_b32_e32 v54, v168, v54, vcc
	v_cmp_neq_f32_e32 vcc, 1.0, v68
	s_waitcnt vmcnt(0) lgkmcnt(0)
	v_lshlrev_b32_e32 v55, 16, v30
	v_cndmask_b32_e32 v54, v169, v54, vcc
	v_cndmask_b32_e64 v54, v54, -v68, s[12:13]
	v_mul_f32_e32 v58, 0x3fb8aa3b, v54
	v_mul_f32_e32 v54, v5, v12
	v_exp_f32_e32 v59, v54
	v_mul_f32_e32 v54, v58, v13
	v_exp_f32_e32 v60, v54
	v_lshlrev_b32_e32 v54, 16, v34
	v_mov_b32_e32 v56, v38
	v_mov_b32_e32 v57, v42
	v_pk_mul_f32 v[56:57], v[56:57], v[54:55]
	v_mul_f32_e32 v5, v5, v15
	v_sub_f32_e32 v61, v57, v56
	v_mov_b32_e32 v56, v42
	v_mov_b32_e32 v57, v38
	v_pk_mul_f32 v[54:55], v[56:57], v[54:55]
	v_mov_b32_e32 v38, v43
	v_add_f32_e32 v62, v54, v55
	v_and_b32_e32 v55, 0xffff0000, v30
	v_and_b32_e32 v54, 0xffff0000, v34
	v_mov_b32_e32 v42, v39
	v_pk_mul_f32 v[38:39], v[38:39], v[54:55]
	v_pk_mul_f32 v[56:57], v[42:43], v[54:55]
	v_add_f32_e32 v54, v38, v39
	v_lshlrev_b32_e32 v39, 16, v31
	v_lshlrev_b32_e32 v38, 16, v35
	v_mov_b32_e32 v42, v40
	v_mov_b32_e32 v43, v44
	v_pk_mul_f32 v[42:43], v[42:43], v[38:39]
	v_and_b32_e32 v31, 0xffff0000, v31
	v_sub_f32_e32 v55, v43, v42
	v_mov_b32_e32 v42, v44
	v_mov_b32_e32 v43, v40
	v_and_b32_e32 v30, 0xffff0000, v35
	v_mov_b32_e32 v44, v41
	v_mov_b32_e32 v40, v45
	v_pk_mul_f32 v[38:39], v[42:43], v[38:39]
	v_pk_mul_f32 v[34:35], v[44:45], v[30:31]
	v_pk_mul_f32 v[30:31], v[40:41], v[30:31]
	v_add_f32_e32 v43, v38, v39
	v_sub_f32_e32 v39, v35, v34
	v_add_f32_e32 v44, v30, v31
	v_lshlrev_b32_e32 v31, 16, v32
	v_lshlrev_b32_e32 v30, 16, v36
; #define LAS __attribute__((address_space(3)))
; DI unsigned pk2(float lo, float hi) { return pg8::cvt_pk_bf16(lo, hi); }
; DI float fexp2(float x) { return __builtin_amdgcn_exp2f(x); }
; DI void ret_kv_phase(const Params& P, LAS unsigned char* lds, int r, const bf16* QKV, bf16* ST) {
;     ...
;         _Pragma("unroll") for (int it_ = 0; it_ < 2; ++it_) { const int task = tid + 512 * it_; const int j = task >> 3, dg = task & 7;
;             const bf16* kp = QKV + (size_t)(tokbase + j) * NIN0 + 1536 + h * 128 + dg * 8;
;             const bf16x8 lo = *(const bf16x8*)kp, hi = *(const bf16x8*)(kp + 64);
;             const float* cp = rc + (size_t)(pos0 + j) * 64 + dg * 8; const float* sp = rsn + (size_t)(pos0 + j) * 64 + dg * 8;
;             const f32x4 c0 = *(const f32x4*)cp, c1 = *(const f32x4*)(cp + 4), s0 = *(const f32x4*)sp, s1 = *(const f32x4*)(sp + 4);
;             const float wf = QK_SCALE * fexp2((float)(127 - j) * l2f), wb = QK_SCALE * fexp2((float)j * l2b);
;             float o1[8], o2[8];
; #pragma unroll
;             for (int e = 0; e < 8; ++e) { const float x1 = bf2f((unsigned short)lo[e]), x2 = bf2f((unsigned short)hi[e]); const float c = e < 4 ? c0[e & 3] : c1[e & 3], s = e < 4 ? s0[e & 3] : s1[e & 3];
;                 o1[e] = x1 * c - x2 * s; o2[e] = x1 * s + x2 * c; }
;             v4u a, b, c, d;
;             a.x = pk2(o1[0] * wf, o1[1] * wf); a.y = pk2(o1[2] * wf, o1[3] * wf); a.z = pk2(o1[4] * wf, o1[5] * wf); a.w = pk2(o1[6] * wf, o1[7] * wf);
;             b.x = pk2(o2[0] * wf, o2[1] * wf); b.y = pk2(o2[2] * wf, o2[3] * wf); b.z = pk2(o2[4] * wf, o2[5] * wf); b.w = pk2(o2[6] * wf, o2[7] * wf);
;             c.x = pk2(o1[0] * wb, o1[1] * wb); c.y = pk2(o1[2] * wb, o1[3] * wb); c.z = pk2(o1[4] * wb, o1[5] * wb); c.w = pk2(o1[6] * wb, o1[7] * wb);
;             d.x = pk2(o2[0] * wb, o2[1] * wb); d.y = pk2(o2[2] * wb, o2[3] * wb); d.z = pk2(o2[4] * wb, o2[5] * wb); d.w = pk2(o2[6] * wb, o2[7] * wb);
;             *(LAS v4u*)(KF + j * PITCH + dg * 16) = a; *(LAS v4u*)(KF + j * PITCH + 128 + dg * 16) = b;
;             *(LAS v4u*)(KB + j * PITCH + dg * 16) = c; *(LAS v4u*)(KB + j * PITCH + 128 + dg * 16) = d; }
	v_mov_b32_e32 v34, v46
	v_mov_b32_e32 v35, v50
	v_pk_mul_f32 v[34:35], v[34:35], v[30:31]
	v_sub_f32_e32 v56, v57, v56
	v_sub_f32_e32 v40, v35, v34
	v_mov_b32_e32 v34, v50
	v_mov_b32_e32 v35, v46
	v_pk_mul_f32 v[30:31], v[34:35], v[30:31]
	v_mov_b32_e32 v50, v47
	v_add_f32_e32 v45, v30, v31
	v_and_b32_e32 v31, 0xffff0000, v32
	v_and_b32_e32 v30, 0xffff0000, v36
	v_mov_b32_e32 v46, v51
	v_pk_mul_f32 v[34:35], v[50:51], v[30:31]
	v_pk_mul_f32 v[30:31], v[46:47], v[30:31]
	v_sub_f32_e32 v41, v35, v34
	v_add_f32_e32 v46, v30, v31
	v_lshlrev_b32_e32 v31, 16, v33
	v_lshlrev_b32_e32 v30, 16, v37
	v_mov_b32_e32 v34, v48
	v_mov_b32_e32 v35, v52
	v_pk_mul_f32 v[34:35], v[34:35], v[30:31]
	v_exp_f32_e32 v5, v5
	v_sub_f32_e32 v42, v35, v34
	v_mov_b32_e32 v34, v52
	v_mov_b32_e32 v35, v48
	v_pk_mul_f32 v[30:31], v[34:35], v[30:31]
	v_mov_b32_e32 v52, v49
	v_add_f32_e32 v47, v30, v31
	v_and_b32_e32 v31, 0xffff0000, v33
	v_and_b32_e32 v30, 0xffff0000, v37
	v_mov_b32_e32 v48, v53
	v_pk_mul_f32 v[32:33], v[52:53], v[30:31]
	v_pk_mul_f32 v[30:31], v[48:49], v[30:31]
	v_mul_f32_e32 v37, 0x3db504f3, v59
	v_add_f32_e32 v48, v30, v31
	v_mul_f32_e32 v30, v61, v37
	v_mul_f32_e32 v31, v56, v37
	v_sub_f32_e32 v50, v33, v32
	v_cvt_pk_bf16_f32 v30, v30, v31
	v_mul_f32_e32 v31, v55, v37
	v_mul_f32_e32 v32, v39, v37
	v_cvt_pk_bf16_f32 v31, v31, v32
	v_mul_f32_e32 v32, v40, v37
	v_mul_f32_e32 v33, v41, v37
	v_cvt_pk_bf16_f32 v32, v32, v33
	v_mul_f32_e32 v33, v42, v37
	v_mul_f32_e32 v34, v50, v37
	v_cvt_pk_bf16_f32 v33, v33, v34
	v_mul_f32_e32 v34, v62, v37
	v_mul_f32_e32 v35, v54, v37
	v_cvt_pk_bf16_f32 v34, v34, v35
	v_mul_f32_e32 v35, v43, v37
	v_mul_f32_e32 v36, v44, v37
	v_cvt_pk_bf16_f32 v35, v35, v36
	v_mul_f32_e32 v36, v45, v37
	v_mul_f32_e32 v38, v46, v37
	v_mul_f32_e32 v49, 0x3db504f3, v60
	v_cvt_pk_bf16_f32 v36, v36, v38
	v_mul_f32_e32 v38, v47, v37
	v_mul_f32_e32 v37, v48, v37
	v_cvt_pk_bf16_f32 v37, v38, v37
	v_mul_f32_e32 v38, v61, v49
	v_mul_f32_e32 v51, v56, v49
	v_mul_f32_e32 v39, v39, v49
	v_mul_f32_e32 v40, v40, v49
	v_mul_f32_e32 v41, v41, v49
	v_cvt_pk_bf16_f32 v38, v38, v51
	v_mul_f32_e32 v51, v55, v49
	v_cvt_pk_bf16_f32 v39, v51, v39
	v_cvt_pk_bf16_f32 v40, v40, v41
	v_mul_f32_e32 v41, v42, v49
	v_mul_f32_e32 v42, v50, v49
	v_cvt_pk_bf16_f32 v41, v41, v42
	v_mul_f32_e32 v42, v62, v49
	v_mul_f32_e32 v43, v43, v49
	v_mul_f32_e32 v44, v44, v49
	v_mul_f32_e32 v50, v54, v49
	v_cvt_pk_bf16_f32 v42, v42, v50
	v_cvt_pk_bf16_f32 v43, v43, v44
	v_mul_f32_e32 v44, v45, v49
	v_mul_f32_e32 v45, v46, v49
	v_cvt_pk_bf16_f32 v44, v44, v45
	v_mul_f32_e32 v45, v47, v49
	v_mul_f32_e32 v46, v48, v49
	v_cvt_pk_bf16_f32 v45, v45, v46
	ds_write_b128 v21, v[30:33]
	ds_write_b128 v21, v[34:37] offset:128
	ds_write_b128 v21, v[38:41] offset:34816
	ds_write_b128 v21, v[42:45] offset:34944
	v_add_u32_e32 v30, s10, v14
	v_mad_i64_i32 v[30:31], s[12:13], v30, s18, v[6:7]
	v_lshl_add_u64 v[30:31], v[30:31], 0, s[4:5]
	v_add_u32_e32 v38, s11, v14
	v_lshl_add_u64 v[34:35], v[30:31], 0, v[128:129]
	v_ashrrev_i32_e32 v39, 31, v38
	flat_load_dwordx4 v[30:33], v[34:35] offset:3072
	s_nop 0
	flat_load_dwordx4 v[34:37], v[34:35] offset:3200
	v_lshlrev_b64 v[38:39], 8, v[38:39]
	v_lshl_add_u64 v[50:51], v[0:1], 0, v[38:39]
	v_lshl_add_u64 v[46:47], v[2:3], 0, v[38:39]
	flat_load_dwordx4 v[38:41], v[46:47]
	flat_load_dwordx4 v[42:45], v[50:51]
	s_nop 0
	flat_load_dwordx4 v[46:49], v[46:47] offset:16
	s_nop 0
	flat_load_dwordx4 v[50:53], v[50:51] offset:16
	v_mul_f32_e32 v54, v58, v16
	v_exp_f32_e32 v58, v54
	v_mul_f32_e32 v5, 0x3db504f3, v5
	s_waitcnt vmcnt(0) lgkmcnt(0)
	v_lshlrev_b32_e32 v55, 16, v30
	v_lshlrev_b32_e32 v54, 16, v34
	v_mov_b32_e32 v56, v38
	v_mov_b32_e32 v57, v42
	v_pk_mul_f32 v[56:57], v[56:57], v[54:55]
	s_nop 0
	v_sub_f32_e32 v59, v57, v56
	v_mov_b32_e32 v56, v42
	v_mov_b32_e32 v57, v38
	v_pk_mul_f32 v[54:55], v[56:57], v[54:55]
	v_mov_b32_e32 v38, v43
	v_add_f32_e32 v60, v54, v55
	v_and_b32_e32 v55, 0xffff0000, v30
	v_and_b32_e32 v54, 0xffff0000, v34
	v_mov_b32_e32 v42, v39
	v_pk_mul_f32 v[38:39], v[38:39], v[54:55]
	v_pk_mul_f32 v[56:57], v[42:43], v[54:55]
	v_add_f32_e32 v54, v38, v39
	v_lshlrev_b32_e32 v39, 16, v31
	v_lshlrev_b32_e32 v38, 16, v35
	v_mov_b32_e32 v42, v40
	v_mov_b32_e32 v43, v44
	v_pk_mul_f32 v[42:43], v[42:43], v[38:39]
	v_and_b32_e32 v31, 0xffff0000, v31
	v_sub_f32_e32 v55, v43, v42
	v_mov_b32_e32 v42, v44
	v_mov_b32_e32 v43, v40
	v_and_b32_e32 v30, 0xffff0000, v35
	v_mov_b32_e32 v44, v41
	v_mov_b32_e32 v40, v45
	v_pk_mul_f32 v[38:39], v[42:43], v[38:39]
	v_pk_mul_f32 v[34:35], v[44:45], v[30:31]
	v_pk_mul_f32 v[30:31], v[40:41], v[30:31]
	v_add_f32_e32 v43, v38, v39
	v_sub_f32_e32 v39, v35, v34
	v_add_f32_e32 v44, v30, v31
	v_lshlrev_b32_e32 v31, 16, v32
	v_lshlrev_b32_e32 v30, 16, v36
	v_mov_b32_e32 v34, v46
	v_mov_b32_e32 v35, v50
	v_pk_mul_f32 v[34:35], v[34:35], v[30:31]
	v_sub_f32_e32 v56, v57, v56
	v_sub_f32_e32 v40, v35, v34
	v_mov_b32_e32 v34, v50
	v_mov_b32_e32 v35, v46
	v_pk_mul_f32 v[30:31], v[34:35], v[30:31]
	v_mov_b32_e32 v50, v47
	v_add_f32_e32 v45, v30, v31
	v_and_b32_e32 v31, 0xffff0000, v32
	v_and_b32_e32 v30, 0xffff0000, v36
	v_mov_b32_e32 v46, v51
	v_pk_mul_f32 v[34:35], v[50:51], v[30:31]
	v_pk_mul_f32 v[30:31], v[46:47], v[30:31]
	v_sub_f32_e32 v41, v35, v34
	v_add_f32_e32 v46, v30, v31
	v_lshlrev_b32_e32 v31, 16, v33
	v_lshlrev_b32_e32 v30, 16, v37
	v_mov_b32_e32 v34, v48
	v_mov_b32_e32 v35, v52
	v_pk_mul_f32 v[34:35], v[34:35], v[30:31]
	v_mul_f32_e32 v36, v44, v5
	v_sub_f32_e32 v42, v35, v34
	v_mov_b32_e32 v34, v52
	v_mov_b32_e32 v35, v48
	v_pk_mul_f32 v[30:31], v[34:35], v[30:31]
	v_mov_b32_e32 v52, v49
; #define LAS __attribute__((address_space(3)))
; DI unsigned pk2(float lo, float hi) { return pg8::cvt_pk_bf16(lo, hi); }
; DI f32x4 mfma16(bf16x8 a, bf16x8 b, f32x4 c) { return __builtin_amdgcn_mfma_f32_16x16x32_bf16(a, b, c, 0, 0, 0); }
; DI void ret_kv_phase(const Params& P, LAS unsigned char* lds, int r, const bf16* QKV, bf16* ST) {
;     ...
;             a.x = pk2(o1[0] * wf, o1[1] * wf); a.y = pk2(o1[2] * wf, o1[3] * wf); a.z = pk2(o1[4] * wf, o1[5] * wf); a.w = pk2(o1[6] * wf, o1[7] * wf);
;             b.x = pk2(o2[0] * wf, o2[1] * wf); b.y = pk2(o2[2] * wf, o2[3] * wf); b.z = pk2(o2[4] * wf, o2[5] * wf); b.w = pk2(o2[6] * wf, o2[7] * wf);
;             c.x = pk2(o1[0] * wb, o1[1] * wb); c.y = pk2(o1[2] * wb, o1[3] * wb); c.z = pk2(o1[4] * wb, o1[5] * wb); c.w = pk2(o1[6] * wb, o1[7] * wb);
;             d.x = pk2(o2[0] * wb, o2[1] * wb); d.y = pk2(o2[2] * wb, o2[3] * wb); d.z = pk2(o2[4] * wb, o2[5] * wb); d.w = pk2(o2[6] * wb, o2[7] * wb);
;             *(LAS v4u*)(KF + j * PITCH + dg * 16) = a; *(LAS v4u*)(KF + j * PITCH + 128 + dg * 16) = b;
;             *(LAS v4u*)(KB + j * PITCH + dg * 16) = c; *(LAS v4u*)(KB + j * PITCH + 128 + dg * 16) = d; }
;         _Pragma("unroll") for (int it_ = 0; it_ < 4; ++it_) { const int task = tid + 512 * it_; const int j = task >> 4, c = task & 15;
;             *(LAS v4u*)(VI + j * PITCH + c * 16) = *(const v4u*)(QKV + (size_t)(tokbase + j) * NIN0 + 3072 + h * 128 + c * 8); }
;         __syncthreads();
;         f32x4 af[8], ab[8];
; #pragma unroll
;         for (int t = 0; t < 8; ++t) { af[t] = (f32x4){0.f, 0.f, 0.f, 0.f}; ab[t] = (f32x4){0.f, 0.f, 0.f, 0.f}; }
; #pragma unroll
;         for (int ks = 0; ks < 4; ++ks) { const bf16x8 kf = frag_tr(KF, PITCH, 32 * ks, 16 * wave, lane), kb = frag_tr(KB, PITCH, 32 * ks, 16 * wave, lane);
; #pragma unroll
;             for (int t = 0; t < 8; ++t) { if ((t & 3) == 0) __builtin_amdgcn_sched_barrier(0); const bf16x8 bv = frag_tr(VI, PITCH, 32 * ks, 16 * t, lane); af[t] = mfma16(bv, kf, af[t]); ab[t] = mfma16(bv, kb, ab[t]); }
;             __builtin_amdgcn_sched_barrier(0); }
	v_add_f32_e32 v47, v30, v31
	v_and_b32_e32 v31, 0xffff0000, v33
	v_and_b32_e32 v30, 0xffff0000, v37
	v_mov_b32_e32 v48, v53
	v_pk_mul_f32 v[32:33], v[52:53], v[30:31]
	v_pk_mul_f32 v[30:31], v[48:49], v[30:31]
	v_sub_f32_e32 v50, v33, v32
	v_add_f32_e32 v48, v30, v31
	v_mul_f32_e32 v30, v59, v5
	v_mul_f32_e32 v31, v56, v5
	v_cvt_pk_bf16_f32 v30, v30, v31
	v_mul_f32_e32 v31, v55, v5
	v_mul_f32_e32 v32, v39, v5
	v_cvt_pk_bf16_f32 v31, v31, v32
	v_mul_f32_e32 v32, v40, v5
	v_mul_f32_e32 v33, v41, v5
	v_cvt_pk_bf16_f32 v32, v32, v33
	v_mul_f32_e32 v33, v42, v5
	v_mul_f32_e32 v34, v50, v5
	v_cvt_pk_bf16_f32 v33, v33, v34
	v_mul_f32_e32 v34, v60, v5
	v_mul_f32_e32 v35, v54, v5
	v_cvt_pk_bf16_f32 v34, v34, v35
	v_mul_f32_e32 v35, v43, v5
	v_cvt_pk_bf16_f32 v35, v35, v36
	v_mul_f32_e32 v36, v45, v5
	v_mul_f32_e32 v37, v46, v5
	v_mul_f32_e32 v49, 0x3db504f3, v58
	v_cvt_pk_bf16_f32 v36, v36, v37
	v_mul_f32_e32 v37, v47, v5
	v_mul_f32_e32 v5, v48, v5
	v_cvt_pk_bf16_f32 v37, v37, v5
	v_mul_f32_e32 v5, v59, v49
	v_mul_f32_e32 v38, v56, v49
	v_cvt_pk_bf16_f32 v38, v5, v38
	v_mul_f32_e32 v5, v55, v49
	v_mul_f32_e32 v39, v39, v49
	v_cvt_pk_bf16_f32 v39, v5, v39
	v_mul_f32_e32 v5, v40, v49
	v_mul_f32_e32 v40, v41, v49
	v_cvt_pk_bf16_f32 v40, v5, v40
	v_mul_f32_e32 v5, v42, v49
	v_mul_f32_e32 v41, v50, v49
	v_cvt_pk_bf16_f32 v41, v5, v41
	v_mul_f32_e32 v5, v60, v49
	v_mul_f32_e32 v42, v54, v49
	v_cvt_pk_bf16_f32 v42, v5, v42
	v_mul_f32_e32 v5, v43, v49
	v_mul_f32_e32 v43, v44, v49
	v_cvt_pk_bf16_f32 v43, v5, v43
	v_mul_f32_e32 v5, v45, v49
	v_mul_f32_e32 v44, v46, v49
	v_cvt_pk_bf16_f32 v44, v5, v44
	v_mul_f32_e32 v5, v47, v49
	v_mul_f32_e32 v45, v48, v49
	v_cvt_pk_bf16_f32 v45, v5, v45
	v_add_u32_e32 v5, s10, v17
	ds_write_b128 v22, v[30:33]
	ds_write_b128 v22, v[34:37] offset:128
	ds_write_b128 v22, v[38:41] offset:34816
	ds_write_b128 v22, v[42:45] offset:34944
	v_mad_i64_i32 v[30:31], s[12:13], v5, s18, v[6:7]
	v_lshl_add_u64 v[30:31], v[30:31], 0, s[4:5]
	v_mov_b32_e32 v5, v129
	v_lshl_add_u64 v[30:31], v[30:31], 0, v[4:5]
	v_add_co_u32_e32 v30, vcc, s40, v30
	s_nop 1
	v_addc_co_u32_e32 v31, vcc, 0, v31, vcc
	flat_load_dwordx4 v[30:33], v[30:31] offset:2048
	s_waitcnt vmcnt(0) lgkmcnt(0)
	ds_write_b128 v23, v[30:33]
	v_add_u32_e32 v30, s10, v18
	v_mad_i64_i32 v[30:31], s[12:13], v30, s18, v[6:7]
	v_lshl_add_u64 v[30:31], v[30:31], 0, s[4:5]
	v_lshl_add_u64 v[30:31], v[30:31], 0, v[4:5]
	v_add_co_u32_e32 v30, vcc, s40, v30
	s_nop 1
	v_addc_co_u32_e32 v31, vcc, 0, v31, vcc
	flat_load_dwordx4 v[30:33], v[30:31] offset:2048
	s_waitcnt vmcnt(0) lgkmcnt(0)
	ds_write_b128 v24, v[30:33]
	v_add_u32_e32 v30, s10, v19
	v_mad_i64_i32 v[30:31], s[12:13], v30, s18, v[6:7]
	v_lshl_add_u64 v[30:31], v[30:31], 0, s[4:5]
	v_lshl_add_u64 v[30:31], v[30:31], 0, v[4:5]
	v_add_co_u32_e32 v30, vcc, s40, v30
	s_nop 1
	v_addc_co_u32_e32 v31, vcc, 0, v31, vcc
	flat_load_dwordx4 v[30:33], v[30:31] offset:2048
	s_waitcnt vmcnt(0) lgkmcnt(0)
	ds_write_b128 v25, v[30:33]
	v_add_u32_e32 v30, s10, v20
	v_mad_i64_i32 v[6:7], s[10:11], v30, s18, v[6:7]
	v_lshl_add_u64 v[6:7], v[6:7], 0, s[4:5]
	v_lshl_add_u64 v[6:7], v[6:7], 0, v[4:5]
	v_add_co_u32_e32 v6, vcc, s40, v6
	s_nop 1
	v_addc_co_u32_e32 v7, vcc, 0, v7, vcc
	flat_load_dwordx4 v[30:33], v[6:7] offset:2048
	s_waitcnt vmcnt(0) lgkmcnt(0)
	ds_write_b128 v26, v[30:33]
	s_waitcnt lgkmcnt(0)
	s_barrier
	ds_read_b64_tr_b16 v[30:31], v27
	ds_read_b64_tr_b16 v[32:33], v27 offset:1088
	ds_read_b64_tr_b16 v[34:35], v27 offset:34816
	ds_read_b64_tr_b16 v[36:37], v27 offset:35904
	ds_read_b64_tr_b16 v[40:41], v10 offset:1088
	ds_read_b64_tr_b16 v[38:39], v10
	ds_read_b64_tr_b16 v[42:43], v10 offset:32
	ds_read_b64_tr_b16 v[46:47], v10 offset:64
	ds_read_b64_tr_b16 v[50:51], v10 offset:96
	ds_read_b64_tr_b16 v[44:45], v10 offset:1120
	ds_read_b64_tr_b16 v[48:49], v10 offset:1152
	ds_read_b64_tr_b16 v[52:53], v10 offset:1184
	s_waitcnt lgkmcnt(6)
	v_mfma_f32_16x16x32_bf16 v[54:57], v[38:41], v[30:33], 0
	v_mfma_f32_16x16x32_bf16 v[38:41], v[38:41], v[34:37], 0
	s_waitcnt lgkmcnt(2)
	v_mfma_f32_16x16x32_bf16 v[58:61], v[42:45], v[30:33], 0
	v_mfma_f32_16x16x32_bf16 v[42:45], v[42:45], v[34:37], 0
	s_waitcnt lgkmcnt(1)
	v_mfma_f32_16x16x32_bf16 v[62:65], v[46:49], v[30:33], 0
	v_mfma_f32_16x16x32_bf16 v[46:49], v[46:49], v[34:37], 0
	s_waitcnt lgkmcnt(0)
	v_mfma_f32_16x16x32_bf16 v[66:69], v[50:53], v[30:33], 0
	v_mfma_f32_16x16x32_bf16 v[50:53], v[50:53], v[34:37], 0
	ds_read_b64_tr_b16 v[72:73], v10 offset:1216
	ds_read_b64_tr_b16 v[70:71], v10 offset:128
	ds_read_b64_tr_b16 v[74:75], v10 offset:160
	ds_read_b64_tr_b16 v[78:79], v10 offset:192
	ds_read_b64_tr_b16 v[82:83], v10 offset:224
	ds_read_b64_tr_b16 v[76:77], v10 offset:1248
	ds_read_b64_tr_b16 v[80:81], v10 offset:1280
	ds_read_b64_tr_b16 v[84:85], v10 offset:1312
	s_waitcnt lgkmcnt(6)
	v_mfma_f32_16x16x32_bf16 v[86:89], v[70:73], v[30:33], 0
	v_mfma_f32_16x16x32_bf16 v[70:73], v[70:73], v[34:37], 0
	s_waitcnt lgkmcnt(2)
	v_mfma_f32_16x16x32_bf16 v[90:93], v[74:77], v[30:33], 0
	v_mfma_f32_16x16x32_bf16 v[74:77], v[74:77], v[34:37], 0
	s_waitcnt lgkmcnt(1)
	v_mfma_f32_16x16x32_bf16 v[94:97], v[78:81], v[30:33], 0
	v_mfma_f32_16x16x32_bf16 v[78:81], v[78:81], v[34:37], 0
	s_waitcnt lgkmcnt(0)
	v_mfma_f32_16x16x32_bf16 v[30:33], v[82:85], v[30:33], 0
	v_mfma_f32_16x16x32_bf16 v[34:37], v[82:85], v[34:37], 0
	ds_read_b64_tr_b16 v[82:83], v27 offset:8704
	ds_read_b64_tr_b16 v[84:85], v27 offset:9792
	ds_read_b64_tr_b16 v[98:99], v27 offset:43520
	ds_read_b64_tr_b16 v[100:101], v27 offset:44608
	ds_read_b64_tr_b16 v[104:105], v10 offset:9792
	ds_read_b64_tr_b16 v[102:103], v10 offset:8704
	ds_read_b64_tr_b16 v[106:107], v10 offset:8736
	ds_read_b64_tr_b16 v[110:111], v10 offset:8768
	ds_read_b64_tr_b16 v[114:115], v10 offset:8800
	ds_read_b64_tr_b16 v[108:109], v10 offset:9824
	ds_read_b64_tr_b16 v[112:113], v10 offset:9856
	ds_read_b64_tr_b16 v[116:117], v10 offset:9888
	s_waitcnt lgkmcnt(6)
; DI f32x4 mfma16(bf16x8 a, bf16x8 b, f32x4 c) { return __builtin_amdgcn_mfma_f32_16x16x32_bf16(a, b, c, 0, 0, 0); }
; DI void ret_kv_phase(const Params& P, LAS unsigned char* lds, int r, const bf16* QKV, bf16* ST) {
;     ...
; #pragma unroll
;         for (int ks = 0; ks < 4; ++ks) { const bf16x8 kf = frag_tr(KF, PITCH, 32 * ks, 16 * wave, lane), kb = frag_tr(KB, PITCH, 32 * ks, 16 * wave, lane);
; #pragma unroll
;             for (int t = 0; t < 8; ++t) { if ((t & 3) == 0) __builtin_amdgcn_sched_barrier(0); const bf16x8 bv = frag_tr(VI, PITCH, 32 * ks, 16 * t, lane); af[t] = mfma16(bv, kf, af[t]); ab[t] = mfma16(bv, kb, ab[t]); }
;             __builtin_amdgcn_sched_barrier(0); }
	v_mfma_f32_16x16x32_bf16 v[54:57], v[102:105], v[82:85], v[54:57]
	v_mfma_f32_16x16x32_bf16 v[38:41], v[102:105], v[98:101], v[38:41]
	s_waitcnt lgkmcnt(2)
	v_mfma_f32_16x16x32_bf16 v[58:61], v[106:109], v[82:85], v[58:61]
	v_mfma_f32_16x16x32_bf16 v[42:45], v[106:109], v[98:101], v[42:45]
	s_waitcnt lgkmcnt(1)
	v_mfma_f32_16x16x32_bf16 v[62:65], v[110:113], v[82:85], v[62:65]
	v_mfma_f32_16x16x32_bf16 v[46:49], v[110:113], v[98:101], v[46:49]
	s_waitcnt lgkmcnt(0)
	v_mfma_f32_16x16x32_bf16 v[66:69], v[114:117], v[82:85], v[66:69]
	v_mfma_f32_16x16x32_bf16 v[50:53], v[114:117], v[98:101], v[50:53]
	ds_read_b64_tr_b16 v[104:105], v10 offset:9920
	ds_read_b64_tr_b16 v[102:103], v10 offset:8832
	ds_read_b64_tr_b16 v[106:107], v10 offset:8864
	ds_read_b64_tr_b16 v[110:111], v10 offset:8896
	ds_read_b64_tr_b16 v[114:115], v10 offset:8928
	ds_read_b64_tr_b16 v[108:109], v10 offset:9952
	ds_read_b64_tr_b16 v[112:113], v10 offset:9984
	ds_read_b64_tr_b16 v[116:117], v10 offset:10016
	s_waitcnt lgkmcnt(6)
	v_mfma_f32_16x16x32_bf16 v[86:89], v[102:105], v[82:85], v[86:89]
	v_mfma_f32_16x16x32_bf16 v[70:73], v[102:105], v[98:101], v[70:73]
	s_waitcnt lgkmcnt(2)
	v_mfma_f32_16x16x32_bf16 v[90:93], v[106:109], v[82:85], v[90:93]
	v_mfma_f32_16x16x32_bf16 v[74:77], v[106:109], v[98:101], v[74:77]
	s_waitcnt lgkmcnt(1)
	v_mfma_f32_16x16x32_bf16 v[94:97], v[110:113], v[82:85], v[94:97]
	v_mfma_f32_16x16x32_bf16 v[78:81], v[110:113], v[98:101], v[78:81]
	s_waitcnt lgkmcnt(0)
	v_mfma_f32_16x16x32_bf16 v[30:33], v[114:117], v[82:85], v[30:33]
	v_mfma_f32_16x16x32_bf16 v[34:37], v[114:117], v[98:101], v[34:37]
	ds_read_b64_tr_b16 v[82:83], v27 offset:17408
	ds_read_b64_tr_b16 v[84:85], v27 offset:18496
	ds_read_b64_tr_b16 v[98:99], v27 offset:52224
	ds_read_b64_tr_b16 v[100:101], v27 offset:53312
	ds_read_b64_tr_b16 v[104:105], v10 offset:18496
	ds_read_b64_tr_b16 v[102:103], v10 offset:17408
	ds_read_b64_tr_b16 v[106:107], v10 offset:17440
	ds_read_b64_tr_b16 v[110:111], v10 offset:17472
	ds_read_b64_tr_b16 v[114:115], v10 offset:17504
	ds_read_b64_tr_b16 v[108:109], v10 offset:18528
	ds_read_b64_tr_b16 v[112:113], v10 offset:18560
	ds_read_b64_tr_b16 v[116:117], v10 offset:18592
	s_waitcnt lgkmcnt(6)
	v_mfma_f32_16x16x32_bf16 v[54:57], v[102:105], v[82:85], v[54:57]
	v_mfma_f32_16x16x32_bf16 v[38:41], v[102:105], v[98:101], v[38:41]
	s_waitcnt lgkmcnt(2)
	v_mfma_f32_16x16x32_bf16 v[58:61], v[106:109], v[82:85], v[58:61]
	v_mfma_f32_16x16x32_bf16 v[42:45], v[106:109], v[98:101], v[42:45]
	s_waitcnt lgkmcnt(1)
	v_mfma_f32_16x16x32_bf16 v[62:65], v[110:113], v[82:85], v[62:65]
	v_mfma_f32_16x16x32_bf16 v[46:49], v[110:113], v[98:101], v[46:49]
	s_waitcnt lgkmcnt(0)
	v_mfma_f32_16x16x32_bf16 v[66:69], v[114:117], v[82:85], v[66:69]
	v_mfma_f32_16x16x32_bf16 v[50:53], v[114:117], v[98:101], v[50:53]
	ds_read_b64_tr_b16 v[104:105], v10 offset:18624
	ds_read_b64_tr_b16 v[102:103], v10 offset:17536
	ds_read_b64_tr_b16 v[106:107], v10 offset:17568
	ds_read_b64_tr_b16 v[110:111], v10 offset:17600
	ds_read_b64_tr_b16 v[114:115], v10 offset:17632
	ds_read_b64_tr_b16 v[108:109], v10 offset:18656
	ds_read_b64_tr_b16 v[112:113], v10 offset:18688
	ds_read_b64_tr_b16 v[116:117], v10 offset:18720
	s_waitcnt lgkmcnt(6)
	v_mfma_f32_16x16x32_bf16 v[86:89], v[102:105], v[82:85], v[86:89]
	v_mfma_f32_16x16x32_bf16 v[70:73], v[102:105], v[98:101], v[70:73]
	s_waitcnt lgkmcnt(2)
	v_mfma_f32_16x16x32_bf16 v[90:93], v[106:109], v[82:85], v[90:93]
	v_mfma_f32_16x16x32_bf16 v[74:77], v[106:109], v[98:101], v[74:77]
	s_waitcnt lgkmcnt(1)
	v_mfma_f32_16x16x32_bf16 v[94:97], v[110:113], v[82:85], v[94:97]
	v_mfma_f32_16x16x32_bf16 v[78:81], v[110:113], v[98:101], v[78:81]
	s_waitcnt lgkmcnt(0)
	v_mfma_f32_16x16x32_bf16 v[30:33], v[114:117], v[82:85], v[30:33]
	v_mfma_f32_16x16x32_bf16 v[34:37], v[114:117], v[98:101], v[34:37]
	ds_read_b64_tr_b16 v[82:83], v27 offset:26112
	ds_read_b64_tr_b16 v[84:85], v27 offset:27200
	ds_read_b64_tr_b16 v[98:99], v27 offset:60928
	ds_read_b64_tr_b16 v[100:101], v27 offset:62016
	ds_read_b64_tr_b16 v[104:105], v10 offset:27200
	ds_read_b64_tr_b16 v[102:103], v10 offset:26112
	ds_read_b64_tr_b16 v[106:107], v10 offset:26144
	ds_read_b64_tr_b16 v[110:111], v10 offset:26176
	ds_read_b64_tr_b16 v[114:115], v10 offset:26208
	ds_read_b64_tr_b16 v[108:109], v10 offset:27232
	ds_read_b64_tr_b16 v[112:113], v10 offset:27264
	ds_read_b64_tr_b16 v[116:117], v10 offset:27296
	s_waitcnt lgkmcnt(6)
	v_mfma_f32_16x16x32_bf16 v[54:57], v[102:105], v[82:85], v[54:57]
	v_mfma_f32_16x16x32_bf16 v[38:41], v[102:105], v[98:101], v[38:41]
	s_waitcnt lgkmcnt(2)
; DI unsigned pk2(float lo, float hi) { return pg8::cvt_pk_bf16(lo, hi); }
; DI f32x4 mfma16(bf16x8 a, bf16x8 b, f32x4 c) { return __builtin_amdgcn_mfma_f32_16x16x32_bf16(a, b, c, 0, 0, 0); }
; DI void ret_kv_phase(const Params& P, LAS unsigned char* lds, int r, const bf16* QKV, bf16* ST) {
;     ...
; #pragma unroll
;         for (int ks = 0; ks < 4; ++ks) { const bf16x8 kf = frag_tr(KF, PITCH, 32 * ks, 16 * wave, lane), kb = frag_tr(KB, PITCH, 32 * ks, 16 * wave, lane);
; #pragma unroll
;             for (int t = 0; t < 8; ++t) { if ((t & 3) == 0) __builtin_amdgcn_sched_barrier(0); const bf16x8 bv = frag_tr(VI, PITCH, 32 * ks, 16 * t, lane); af[t] = mfma16(bv, kf, af[t]); ab[t] = mfma16(bv, kb, ab[t]); }
;             __builtin_amdgcn_sched_barrier(0); }
;         bf16* sf = ST + ((size_t)(0 * 128 + n) * NTH + h) * 16384; bf16* sb = ST + ((size_t)(1 * 128 + n) * NTH + h) * 16384;
; #pragma unroll
;         for (int t = 0; t < 8; ++t)
;         { const int o = (16 * wave + li) * 128 + 16 * t + 4 * g; v2u wf, wb; wf.x = pk2(af[t][0], af[t][1]); wf.y = pk2(af[t][2], af[t][3]); wb.x = pk2(ab[t][0], ab[t][1]); wb.y = pk2(ab[t][2], ab[t][3]);
;             *(v2u*)(sf + o) = wf; *(v2u*)(sb + o) = wb; }
	v_mfma_f32_16x16x32_bf16 v[58:61], v[106:109], v[82:85], v[58:61]
	v_mfma_f32_16x16x32_bf16 v[42:45], v[106:109], v[98:101], v[42:45]
	s_waitcnt lgkmcnt(1)
	v_mfma_f32_16x16x32_bf16 v[62:65], v[110:113], v[82:85], v[62:65]
	v_mfma_f32_16x16x32_bf16 v[46:49], v[110:113], v[98:101], v[46:49]
	s_waitcnt lgkmcnt(0)
	v_mfma_f32_16x16x32_bf16 v[66:69], v[114:117], v[82:85], v[66:69]
	v_mfma_f32_16x16x32_bf16 v[50:53], v[114:117], v[98:101], v[50:53]
	ds_read_b64_tr_b16 v[104:105], v10 offset:27328
	ds_read_b64_tr_b16 v[102:103], v10 offset:26240
	ds_read_b64_tr_b16 v[106:107], v10 offset:26272
	ds_read_b64_tr_b16 v[110:111], v10 offset:26304
	ds_read_b64_tr_b16 v[114:115], v10 offset:26336
	ds_read_b64_tr_b16 v[108:109], v10 offset:27360
	ds_read_b64_tr_b16 v[112:113], v10 offset:27392
	ds_read_b64_tr_b16 v[116:117], v10 offset:27424
	s_waitcnt lgkmcnt(6)
	v_mfma_f32_16x16x32_bf16 v[86:89], v[102:105], v[82:85], v[86:89]
	v_mfma_f32_16x16x32_bf16 v[70:73], v[102:105], v[98:101], v[70:73]
	s_waitcnt lgkmcnt(2)
	v_mfma_f32_16x16x32_bf16 v[90:93], v[106:109], v[82:85], v[90:93]
	v_mfma_f32_16x16x32_bf16 v[74:77], v[106:109], v[98:101], v[74:77]
	s_waitcnt lgkmcnt(1)
	v_mfma_f32_16x16x32_bf16 v[94:97], v[110:113], v[82:85], v[94:97]
	v_mfma_f32_16x16x32_bf16 v[78:81], v[110:113], v[98:101], v[78:81]
	s_waitcnt lgkmcnt(0)
	v_mfma_f32_16x16x32_bf16 v[30:33], v[114:117], v[82:85], v[30:33]
	v_mfma_f32_16x16x32_bf16 v[34:37], v[114:117], v[98:101], v[34:37]
	s_mul_hi_i32 s5, s9, 12
	s_add_u32 s4, s8, s6
	s_addc_u32 s5, s5, s7
	s_lshl_b64 s[4:5], s[4:5], 15
	s_add_u32 s4, s58, s4
	s_addc_u32 s5, s59, s5
	s_addk_i32 s9, 0x80
	s_addk_i32 s8, 0x600
	s_mul_hi_i32 s9, s9, 12
	s_add_u32 s6, s8, s6
	s_addc_u32 s7, s9, s7
	v_lshlrev_b32_e32 v5, 7, v29
	v_lshlrev_b32_e32 v6, 2, v28
	s_lshl_b64 s[6:7], s[6:7], 15
	v_add3_u32 v6, v5, s2, v6
	s_add_u32 s6, s58, s6
	v_ashrrev_i32_e32 v7, 31, v6
	s_addc_u32 s7, s59, s7
	v_lshlrev_b64 v[6:7], 1, v[6:7]
	v_and_b32_e32 v112, 1, v28
	v_mov_b32_e32 v113, 0
	v_mul_u32_u24_e32 v112, 24, v112
	v_lshl_add_u64 v[108:109], s[4:5], 0, v[6:7]
	v_lshl_add_u64 v[110:111], s[6:7], 0, v[6:7]
	v_lshl_add_u64 v[108:109], v[108:109], 0, v[112:113]
	v_lshl_add_u64 v[110:111], v[110:111], 0, v[112:113]
	v_cvt_pk_bf16_f32 v100, v54, v55
	v_cvt_pk_bf16_f32 v101, v56, v57
	v_cvt_pk_bf16_f32 v102, v58, v59
	v_cvt_pk_bf16_f32 v103, v60, v61
	s_nop 1
	v_permlane16_swap_b32_e32 v100, v102
	v_permlane16_swap_b32_e32 v101, v103
	global_store_dwordx4 v[108:109], v[100:103], off
	v_cvt_pk_bf16_f32 v104, v38, v39
	v_cvt_pk_bf16_f32 v105, v40, v41
	v_cvt_pk_bf16_f32 v106, v42, v43
	v_cvt_pk_bf16_f32 v107, v44, v45
	s_nop 1
	v_permlane16_swap_b32_e32 v104, v106
	v_permlane16_swap_b32_e32 v105, v107
	global_store_dwordx4 v[110:111], v[104:107], off
	v_cvt_pk_bf16_f32 v100, v62, v63
	v_cvt_pk_bf16_f32 v101, v64, v65
	v_cvt_pk_bf16_f32 v102, v66, v67
	v_cvt_pk_bf16_f32 v103, v68, v69
	s_nop 1
	v_permlane16_swap_b32_e32 v100, v102
	v_permlane16_swap_b32_e32 v101, v103
	global_store_dwordx4 v[108:109], v[100:103], off offset:64
	v_cvt_pk_bf16_f32 v104, v46, v47
	v_cvt_pk_bf16_f32 v105, v48, v49
	v_cvt_pk_bf16_f32 v106, v50, v51
	v_cvt_pk_bf16_f32 v107, v52, v53
	s_nop 1
	v_permlane16_swap_b32_e32 v104, v106
	v_permlane16_swap_b32_e32 v105, v107
	global_store_dwordx4 v[110:111], v[104:107], off offset:64
	v_cvt_pk_bf16_f32 v100, v86, v87
	v_cvt_pk_bf16_f32 v101, v88, v89
	v_cvt_pk_bf16_f32 v102, v90, v91
	v_cvt_pk_bf16_f32 v103, v92, v93
	s_nop 1
	v_permlane16_swap_b32_e32 v100, v102
	v_permlane16_swap_b32_e32 v101, v103
	global_store_dwordx4 v[108:109], v[100:103], off offset:128
	v_cvt_pk_bf16_f32 v104, v70, v71
	v_cvt_pk_bf16_f32 v105, v72, v73
	v_cvt_pk_bf16_f32 v106, v74, v75
	v_cvt_pk_bf16_f32 v107, v76, v77
	s_nop 1
	v_permlane16_swap_b32_e32 v104, v106
	v_permlane16_swap_b32_e32 v105, v107
	global_store_dwordx4 v[110:111], v[104:107], off offset:128
	v_cvt_pk_bf16_f32 v100, v94, v95
	v_cvt_pk_bf16_f32 v101, v96, v97
	v_cvt_pk_bf16_f32 v102, v30, v31
	v_cvt_pk_bf16_f32 v103, v32, v33
	s_nop 1
	v_permlane16_swap_b32_e32 v100, v102
	v_permlane16_swap_b32_e32 v101, v103
	global_store_dwordx4 v[108:109], v[100:103], off offset:192
	v_cvt_pk_bf16_f32 v104, v78, v79
	v_cvt_pk_bf16_f32 v105, v80, v81
	v_cvt_pk_bf16_f32 v106, v34, v35
	v_cvt_pk_bf16_f32 v107, v36, v37
	s_nop 1
	v_permlane16_swap_b32_e32 v104, v106
	v_permlane16_swap_b32_e32 v105, v107
	global_store_dwordx4 v[110:111], v[104:107], off offset:192
	s_mov_b32 s4, s42
	s_waitcnt lgkmcnt(0)
	s_barrier
	s_add_i32 s0, s4, s0
	s_cmpk_gt_i32 s0, 0x5ff
	s_cbranch_scc0 .LBB0_249
